# FFT forward radix-16 passes: butterflies list-scheduled with renamed temporaries (independent butterflies interleaved, no wait-state nops), arithmetic unchanged
# speedup vs baseline: 1.0309x; 1.0013x over previous
.LBB0_646:
	v_and_or_b32 v140, v111, s42, v0
	v_or_b32_e32 v128, 0x200, v140
	v_ashrrev_i32_e32 v114, 5, v140
	v_lshl_add_u32 v141, v140, 3, 0
	v_ashrrev_i32_e32 v128, 5, v128
	v_lshl_add_u32 v152, v114, 3, v141
	v_or_b32_e32 v114, 64, v140
	v_or_b32_e32 v116, 0x80, v140
	v_or_b32_e32 v118, 0xc0, v140
	v_or_b32_e32 v120, 0x100, v140
	v_or_b32_e32 v122, 0x140, v140
	v_or_b32_e32 v124, 0x180, v140
	v_or_b32_e32 v126, 0x1c0, v140
	v_lshl_add_u32 v160, v128, 3, v141
	v_or_b32_e32 v128, 0x240, v140
	v_or_b32_e32 v130, 0x280, v140
	v_or_b32_e32 v132, 0x2c0, v140
	v_or_b32_e32 v134, 0x300, v140
	v_or_b32_e32 v136, 0x340, v140
	v_or_b32_e32 v138, 0x380, v140
	v_or_b32_e32 v140, 0x3c0, v140
	v_ashrrev_i32_e32 v114, 5, v114
	v_ashrrev_i32_e32 v116, 5, v116
	v_ashrrev_i32_e32 v118, 5, v118
	v_ashrrev_i32_e32 v120, 5, v120
	v_ashrrev_i32_e32 v122, 5, v122
	v_ashrrev_i32_e32 v124, 5, v124
	v_ashrrev_i32_e32 v126, 5, v126
	v_ashrrev_i32_e32 v128, 5, v128
	v_ashrrev_i32_e32 v130, 5, v130
	v_ashrrev_i32_e32 v132, 5, v132
	v_ashrrev_i32_e32 v134, 5, v134
	v_ashrrev_i32_e32 v136, 5, v136
	v_ashrrev_i32_e32 v138, 5, v138
	v_ashrrev_i32_e32 v140, 5, v140
	v_lshl_add_u32 v153, v114, 3, v141
	v_lshl_add_u32 v154, v116, 3, v141
	v_lshl_add_u32 v155, v118, 3, v141
	v_lshl_add_u32 v156, v120, 3, v141
	v_lshl_add_u32 v157, v122, 3, v141
	v_lshl_add_u32 v158, v124, 3, v141
	v_lshl_add_u32 v159, v126, 3, v141
	v_lshl_add_u32 v161, v128, 3, v141
	v_lshl_add_u32 v162, v130, 3, v141
	v_lshl_add_u32 v163, v132, 3, v141
	v_lshl_add_u32 v164, v134, 3, v141
	v_lshl_add_u32 v165, v136, 3, v141
	v_lshl_add_u32 v166, v138, 3, v141
	v_lshl_add_u32 v167, v140, 3, v141
	ds_read_b64 v[114:115], v153 offset:512
	ds_read_b64 v[116:117], v154 offset:1024
	ds_read_b64 v[118:119], v155 offset:1536
	ds_read_b64 v[120:121], v156 offset:2048
	ds_read_b64 v[122:123], v157 offset:2560
	ds_read_b64 v[124:125], v158 offset:3072
	ds_read_b64 v[126:127], v159 offset:3584
	ds_read_b64 v[128:129], v161 offset:4608
	ds_read_b64 v[130:131], v162 offset:5120
	ds_read_b64 v[132:133], v163 offset:5632
	ds_read_b64 v[134:135], v164 offset:6144
	ds_read_b64 v[136:137], v165 offset:6656
	ds_read_b64 v[138:139], v166 offset:7168
	ds_read_b64 v[140:141], v167 offset:7680
	ds_read_b64 v[142:143], v160 offset:4096
	ds_read_b64 v[144:145], v152
	v_add_u32_e32 v25, 0x200, v25
	v_cmp_lt_i32_e32 vcc, s35, v25
	v_add_u32_e32 v111, 0x2000, v111
	s_or_b64 s[10:11], vcc, s[10:11]
	s_waitcnt lgkmcnt(0)
	v_pk_add_f32 v[146:147], v[144:145], v[142:143] neg_lo:[0,1] neg_hi:[0,1]
	v_pk_add_f32 v[148:149], v[114:115], v[128:129] neg_lo:[0,1] neg_hi:[0,1]
	v_pk_add_f32 v[150:151], v[116:117], v[130:131] neg_lo:[0,1] neg_hi:[0,1]
	v_pk_add_f32 v[236:237], v[118:119], v[132:133] neg_lo:[0,1] neg_hi:[0,1]
	v_pk_add_f32 v[238:239], v[120:121], v[134:135] neg_lo:[0,1] neg_hi:[0,1]
	v_pk_add_f32 v[240:241], v[122:123], v[136:137] neg_lo:[0,1] neg_hi:[0,1]
	v_pk_add_f32 v[242:243], v[124:125], v[138:139] neg_lo:[0,1] neg_hi:[0,1]
	v_pk_add_f32 v[244:245], v[126:127], v[140:141] neg_lo:[0,1] neg_hi:[0,1]
	v_pk_mul_f32 v[246:247], v[20:21], v[146:147] op_sel:[0,1] op_sel_hi:[1,0]
	v_pk_add_f32 v[142:143], v[142:143], v[144:145]
	v_pk_mul_f32 v[144:145], v[40:41], v[148:149] op_sel:[0,1] op_sel_hi:[1,0]
	v_pk_fma_f32 v[146:147], v[2:3], v[146:147], v[246:247] neg_hi:[0,0,1]
	v_pk_mul_f32 v[246:247], v[44:45], v[150:151] op_sel:[0,1] op_sel_hi:[1,0]
	v_pk_add_f32 v[114:115], v[114:115], v[128:129]
	v_pk_mul_f32 v[128:129], v[48:49], v[236:237] op_sel:[0,1] op_sel_hi:[1,0]
	v_pk_fma_f32 v[144:145], v[38:39], v[148:149], v[144:145] neg_lo:[0,0,1]
	v_pk_mul_f32 v[148:149], v[52:53], v[238:239] op_sel:[0,1] op_sel_hi:[1,0]
	v_pk_add_f32 v[116:117], v[116:117], v[130:131]
	v_pk_mul_f32 v[130:131], v[22:23], v[240:241] op_sel:[0,1] op_sel_hi:[1,0]
	v_pk_fma_f32 v[150:151], v[42:43], v[150:151], v[246:247] neg_lo:[0,0,1]
	v_pk_mul_f32 v[246:247], v[34:35], v[242:243] op_sel:[0,1] op_sel_hi:[1,0]
	v_pk_add_f32 v[118:119], v[118:119], v[132:133]
	v_pk_mul_f32 v[132:133], v[58:59], v[244:245] op_sel:[0,1] op_sel_hi:[1,0]
	v_pk_fma_f32 v[128:129], v[32:33], v[236:237], v[128:129] neg_lo:[0,0,1]
	v_pk_add_f32 v[120:121], v[120:121], v[134:135]
	v_pk_fma_f32 v[134:135], v[50:51], v[238:239], v[148:149] neg_lo:[0,0,1]
	v_pk_add_f32 v[122:123], v[122:123], v[136:137]
	v_pk_fma_f32 v[136:137], v[46:47], v[240:241], v[130:131] neg_lo:[0,0,1]
	v_pk_add_f32 v[124:125], v[124:125], v[138:139]
	v_pk_fma_f32 v[138:139], v[36:37], v[242:243], v[246:247] neg_lo:[0,0,1]
	v_pk_add_f32 v[126:127], v[126:127], v[140:141]
	v_pk_fma_f32 v[140:141], v[30:31], v[244:245], v[132:133] neg_lo:[0,0,1]
	v_pk_add_f32 v[130:131], v[142:143], v[120:121] neg_lo:[0,1] neg_hi:[0,1]
	v_pk_add_f32 v[132:133], v[114:115], v[122:123] neg_lo:[0,1] neg_hi:[0,1]
	v_pk_add_f32 v[148:149], v[116:117], v[124:125] neg_lo:[0,1] neg_hi:[0,1]
	v_pk_add_f32 v[236:237], v[118:119], v[126:127] neg_lo:[0,1] neg_hi:[0,1]
	v_pk_add_f32 v[238:239], v[146:147], v[134:135] neg_lo:[0,1] neg_hi:[0,1]
	v_pk_add_f32 v[240:241], v[144:145], v[136:137] neg_lo:[0,1] neg_hi:[0,1]
	v_pk_add_f32 v[242:243], v[150:151], v[138:139] neg_lo:[0,1] neg_hi:[0,1]
	v_pk_add_f32 v[244:245], v[128:129], v[140:141] neg_lo:[0,1] neg_hi:[0,1]
	v_pk_mul_f32 v[246:247], v[56:57], v[130:131]
	v_pk_add_f32 v[120:121], v[120:121], v[142:143]
	v_pk_mul_f32 v[142:143], v[66:67], v[132:133]
	v_pk_fma_f32 v[130:131], v[54:55], v[130:131], v[246:247] op_sel:[0,0,1] op_sel_hi:[1,1,0] neg_hi:[0,0,1]
	v_pk_mul_f32 v[246:247], v[70:71], v[148:149]
	v_pk_add_f32 v[114:115], v[114:115], v[122:123]
	v_pk_mul_f32 v[122:123], v[60:61], v[236:237]
	v_pk_fma_f32 v[142:143], v[64:65], v[132:133], v[142:143] op_sel:[0,0,1] op_sel_hi:[1,1,0] neg_lo:[0,0,1]
	v_pk_mul_f32 v[132:133], v[56:57], v[238:239]
	v_pk_add_f32 v[116:117], v[116:117], v[124:125]
	v_pk_mul_f32 v[124:125], v[66:67], v[240:241]
	v_pk_fma_f32 v[148:149], v[68:69], v[148:149], v[246:247] op_sel:[0,0,1] op_sel_hi:[1,1,0] neg_lo:[0,0,1]
	v_pk_mul_f32 v[246:247], v[70:71], v[242:243]
	v_pk_add_f32 v[118:119], v[118:119], v[126:127]
	v_pk_mul_f32 v[126:127], v[60:61], v[244:245]
	v_pk_fma_f32 v[122:123], v[62:63], v[236:237], v[122:123] op_sel:[0,0,1] op_sel_hi:[1,1,0] neg_lo:[0,0,1]
	v_pk_add_f32 v[134:135], v[134:135], v[146:147]
	v_pk_fma_f32 v[132:133], v[54:55], v[238:239], v[132:133] op_sel:[0,0,1] op_sel_hi:[1,1,0] neg_hi:[0,0,1]
	v_pk_add_f32 v[136:137], v[144:145], v[136:137]
	v_pk_fma_f32 v[144:145], v[64:65], v[240:241], v[124:125] op_sel:[0,0,1] op_sel_hi:[1,1,0] neg_lo:[0,0,1]
	v_pk_add_f32 v[124:125], v[150:151], v[138:139]
	v_pk_fma_f32 v[138:139], v[68:69], v[242:243], v[246:247] op_sel:[0,0,1] op_sel_hi:[1,1,0] neg_lo:[0,0,1]
	v_pk_add_f32 v[128:129], v[128:129], v[140:141]
	v_pk_fma_f32 v[140:141], v[62:63], v[244:245], v[126:127] op_sel:[0,0,1] op_sel_hi:[1,1,0] neg_lo:[0,0,1]
	v_pk_add_f32 v[126:127], v[120:121], v[116:117] neg_lo:[0,1] neg_hi:[0,1]
	v_pk_add_f32 v[146:147], v[114:115], v[118:119] neg_lo:[0,1] neg_hi:[0,1]
	v_pk_add_f32 v[150:151], v[130:131], v[148:149] neg_lo:[0,1] neg_hi:[0,1]
	v_pk_add_f32 v[236:237], v[142:143], v[122:123] neg_lo:[0,1] neg_hi:[0,1]
	v_pk_add_f32 v[238:239], v[134:135], v[124:125] neg_lo:[0,1] neg_hi:[0,1]
	v_pk_add_f32 v[240:241], v[136:137], v[128:129] neg_lo:[0,1] neg_hi:[0,1]
	v_pk_add_f32 v[242:243], v[132:133], v[138:139] neg_lo:[0,1] neg_hi:[0,1]
	v_pk_add_f32 v[244:245], v[144:145], v[140:141] neg_lo:[0,1] neg_hi:[0,1]
	v_pk_mul_f32 v[246:247], v[74:75], v[126:127]
	v_pk_add_f32 v[116:117], v[116:117], v[120:121]
	v_pk_mul_f32 v[120:121], v[78:79], v[146:147]
	v_pk_fma_f32 v[126:127], v[72:73], v[126:127], v[246:247] op_sel:[0,0,1] op_sel_hi:[1,1,0] neg_hi:[0,0,1]
	v_pk_mul_f32 v[246:247], v[74:75], v[150:151]
	v_pk_add_f32 v[114:115], v[114:115], v[118:119]
	v_pk_mul_f32 v[118:119], v[78:79], v[236:237]
	v_pk_fma_f32 v[120:121], v[76:77], v[146:147], v[120:121] op_sel:[0,0,1] op_sel_hi:[1,1,0] neg_lo:[0,0,1]
	v_pk_mul_f32 v[146:147], v[74:75], v[238:239]
	v_pk_add_f32 v[130:131], v[148:149], v[130:131]
	v_pk_mul_f32 v[148:149], v[78:79], v[240:241]
	v_pk_fma_f32 v[150:151], v[72:73], v[150:151], v[246:247] op_sel:[0,0,1] op_sel_hi:[1,1,0] neg_hi:[0,0,1]
	v_pk_mul_f32 v[246:247], v[74:75], v[242:243]
	v_pk_add_f32 v[122:123], v[142:143], v[122:123]
	v_pk_mul_f32 v[142:143], v[78:79], v[244:245]
	v_pk_fma_f32 v[118:119], v[76:77], v[236:237], v[118:119] op_sel:[0,0,1] op_sel_hi:[1,1,0] neg_lo:[0,0,1]
	v_pk_add_f32 v[124:125], v[124:125], v[134:135]
	v_pk_fma_f32 v[134:135], v[72:73], v[238:239], v[146:147] op_sel:[0,0,1] op_sel_hi:[1,1,0] neg_hi:[0,0,1]
	v_pk_add_f32 v[128:129], v[136:137], v[128:129]
	v_pk_fma_f32 v[136:137], v[76:77], v[240:241], v[148:149] op_sel:[0,0,1] op_sel_hi:[1,1,0] neg_lo:[0,0,1]
	v_pk_add_f32 v[132:133], v[138:139], v[132:133]
	v_pk_fma_f32 v[148:149], v[72:73], v[242:243], v[246:247] op_sel:[0,0,1] op_sel_hi:[1,1,0] neg_hi:[0,0,1]
	v_pk_add_f32 v[138:139], v[144:145], v[140:141]
	v_pk_fma_f32 v[144:145], v[76:77], v[244:245], v[142:143] op_sel:[0,0,1] op_sel_hi:[1,1,0] neg_lo:[0,0,1]
	v_pk_add_f32 v[140:141], v[116:117], v[114:115] neg_lo:[0,1] neg_hi:[0,1]
	v_pk_add_f32 v[142:143], v[126:127], v[120:121] neg_lo:[0,1] neg_hi:[0,1]
	v_pk_add_f32 v[146:147], v[130:131], v[122:123] neg_lo:[0,1] neg_hi:[0,1]
	v_pk_add_f32 v[236:237], v[150:151], v[118:119] neg_lo:[0,1] neg_hi:[0,1]
	v_pk_add_f32 v[238:239], v[124:125], v[128:129] neg_lo:[0,1] neg_hi:[0,1]
	v_pk_add_f32 v[240:241], v[134:135], v[136:137] neg_lo:[0,1] neg_hi:[0,1]
	v_pk_add_f32 v[242:243], v[132:133], v[138:139] neg_lo:[0,1] neg_hi:[0,1]
	v_pk_add_f32 v[244:245], v[148:149], v[144:145] neg_lo:[0,1] neg_hi:[0,1]
	v_pk_mul_f32 v[246:247], v[82:83], v[140:141]
	v_pk_add_f32 v[114:115], v[114:115], v[116:117]
	v_pk_mul_f32 v[116:117], v[82:83], v[142:143]
	v_pk_fma_f32 v[140:141], v[80:81], v[140:141], v[246:247] op_sel:[0,0,1] op_sel_hi:[1,1,0] neg_hi:[0,0,1]
	v_pk_mul_f32 v[246:247], v[82:83], v[146:147]
	v_pk_add_f32 v[120:121], v[120:121], v[126:127]
	v_pk_mul_f32 v[126:127], v[82:83], v[236:237]
	v_pk_fma_f32 v[116:117], v[80:81], v[142:143], v[116:117] op_sel:[0,0,1] op_sel_hi:[1,1,0] neg_hi:[0,0,1]
	v_pk_mul_f32 v[142:143], v[82:83], v[238:239]
	v_pk_add_f32 v[122:123], v[122:123], v[130:131]
	v_pk_mul_f32 v[130:131], v[82:83], v[240:241]
	v_pk_fma_f32 v[146:147], v[80:81], v[146:147], v[246:247] op_sel:[0,0,1] op_sel_hi:[1,1,0] neg_hi:[0,0,1]
	v_pk_mul_f32 v[246:247], v[82:83], v[242:243]
	v_pk_add_f32 v[118:119], v[118:119], v[150:151]
	v_pk_mul_f32 v[150:151], v[82:83], v[244:245]
	v_pk_fma_f32 v[126:127], v[80:81], v[236:237], v[126:127] op_sel:[0,0,1] op_sel_hi:[1,1,0] neg_hi:[0,0,1]
	v_pk_add_f32 v[124:125], v[128:129], v[124:125]
	v_pk_fma_f32 v[142:143], v[80:81], v[238:239], v[142:143] op_sel:[0,0,1] op_sel_hi:[1,1,0] neg_hi:[0,0,1]
	v_pk_add_f32 v[128:129], v[136:137], v[134:135]
	v_pk_fma_f32 v[134:135], v[80:81], v[240:241], v[130:131] op_sel:[0,0,1] op_sel_hi:[1,1,0] neg_hi:[0,0,1]
	v_pk_add_f32 v[130:131], v[138:139], v[132:133]
	v_pk_fma_f32 v[132:133], v[80:81], v[242:243], v[246:247] op_sel:[0,0,1] op_sel_hi:[1,1,0] neg_hi:[0,0,1]
	v_pk_add_f32 v[136:137], v[144:145], v[148:149]
	v_pk_fma_f32 v[144:145], v[80:81], v[244:245], v[150:151] op_sel:[0,0,1] op_sel_hi:[1,1,0] neg_hi:[0,0,1]
	ds_write_b64 v152, v[114:115]
	ds_write_b64 v153, v[140:141] offset:512
	ds_write_b64 v154, v[120:121] offset:1024
	ds_write_b64 v155, v[116:117] offset:1536
	ds_write_b64 v156, v[122:123] offset:2048
	ds_write_b64 v157, v[146:147] offset:2560
	ds_write_b64 v158, v[118:119] offset:3072
	ds_write_b64 v159, v[126:127] offset:3584
	ds_write_b64 v160, v[124:125] offset:4096
	ds_write_b64 v161, v[142:143] offset:4608
	ds_write_b64 v162, v[128:129] offset:5120
	ds_write_b64 v163, v[134:135] offset:5632
	ds_write_b64 v164, v[130:131] offset:6144
	ds_write_b64 v165, v[132:133] offset:6656
	ds_write_b64 v166, v[136:137] offset:7168
	ds_write_b64 v167, v[144:145] offset:7680
	s_andn2_b64 exec, exec, s[10:11]
	s_cbranch_execnz .LBB0_646

.LBB0_649:
	v_and_b32_e32 v130, 0xffffffc0, v111
	v_or_b32_e32 v114, v130, v0
	v_lshl_add_u32 v131, v114, 3, 0
	v_ashrrev_i32_e32 v114, 2, v130
	v_or_b32_e32 v130, 32, v130
	v_ashrrev_i32_e32 v130, 5, v130
	v_add_u32_e32 v152, v131, v114
	v_lshl_add_u32 v153, v130, 3, v131
	ds_read2_b64 v[114:117], v152 offset1:4
	ds_read2_b64 v[118:121], v152 offset0:8 offset1:12
	ds_read2_b64 v[122:125], v152 offset0:16 offset1:20
	ds_read2_b64 v[126:129], v152 offset0:24 offset1:28
	ds_read2_b64 v[130:133], v153 offset0:32 offset1:36
	ds_read2_b64 v[134:137], v153 offset0:40 offset1:44
	ds_read2_b64 v[138:141], v153 offset0:48 offset1:52
	ds_read2_b64 v[142:145], v153 offset0:56 offset1:60
	v_add_u32_e32 v25, 0x200, v25
	s_waitcnt lgkmcnt(3)
	v_pk_add_f32 v[146:147], v[130:131], v[114:115]
	v_pk_add_f32 v[114:115], v[114:115], v[130:131] neg_lo:[0,1] neg_hi:[0,1]
	v_cmp_lt_i32_e32 vcc, s35, v25
	v_pk_mul_f32 v[130:131], v[20:21], v[114:115] op_sel:[0,1] op_sel_hi:[1,0]
	v_add_u32_e32 v111, 0x2000, v111
	v_pk_fma_f32 v[148:149], v[2:3], v[114:115], v[130:131] neg_hi:[0,0,1]
	s_or_b64 s[10:11], vcc, s[10:11]
	v_pk_add_f32 v[114:115], v[116:117], v[132:133]
	v_pk_add_f32 v[116:117], v[116:117], v[132:133] neg_lo:[0,1] neg_hi:[0,1]
	s_nop 0
	v_pk_mul_f32 v[130:131], v[40:41], v[116:117] op_sel:[0,1] op_sel_hi:[1,0]
	s_nop 0
	v_pk_fma_f32 v[132:133], v[38:39], v[116:117], v[130:131] neg_lo:[0,0,1]
	s_waitcnt lgkmcnt(2)
	v_pk_add_f32 v[116:117], v[118:119], v[134:135]
	v_pk_add_f32 v[118:119], v[118:119], v[134:135] neg_lo:[0,1] neg_hi:[0,1]
	s_nop 0
	v_pk_mul_f32 v[130:131], v[44:45], v[118:119] op_sel:[0,1] op_sel_hi:[1,0]
	s_nop 0
	v_pk_fma_f32 v[134:135], v[42:43], v[118:119], v[130:131] neg_lo:[0,0,1]
	v_pk_add_f32 v[118:119], v[120:121], v[136:137]
	v_pk_add_f32 v[120:121], v[120:121], v[136:137] neg_lo:[0,1] neg_hi:[0,1]
	s_nop 0
	v_pk_mul_f32 v[130:131], v[48:49], v[120:121] op_sel:[0,1] op_sel_hi:[1,0]
	s_nop 0
	v_pk_fma_f32 v[136:137], v[32:33], v[120:121], v[130:131] neg_lo:[0,0,1]
	s_waitcnt lgkmcnt(1)
	v_pk_add_f32 v[120:121], v[122:123], v[138:139]
	v_pk_add_f32 v[122:123], v[122:123], v[138:139] neg_lo:[0,1] neg_hi:[0,1]
	s_nop 0
	v_pk_mul_f32 v[130:131], v[52:53], v[122:123] op_sel:[0,1] op_sel_hi:[1,0]
	s_nop 0
	v_pk_fma_f32 v[138:139], v[50:51], v[122:123], v[130:131] neg_lo:[0,0,1]
	v_pk_add_f32 v[122:123], v[124:125], v[140:141]
	v_pk_add_f32 v[124:125], v[124:125], v[140:141] neg_lo:[0,1] neg_hi:[0,1]
	s_nop 0
	v_pk_mul_f32 v[130:131], v[22:23], v[124:125] op_sel:[0,1] op_sel_hi:[1,0]
	s_nop 0
	v_pk_fma_f32 v[140:141], v[46:47], v[124:125], v[130:131] neg_lo:[0,0,1]
	s_waitcnt lgkmcnt(0)
	v_pk_add_f32 v[124:125], v[126:127], v[142:143] neg_lo:[0,1] neg_hi:[0,1]
	v_pk_add_f32 v[130:131], v[128:129], v[144:145] neg_lo:[0,1] neg_hi:[0,1]
	v_pk_mul_f32 v[150:151], v[34:35], v[124:125] op_sel:[0,1] op_sel_hi:[1,0]
	v_pk_mul_f32 v[236:237], v[58:59], v[130:131] op_sel:[0,1] op_sel_hi:[1,0]
	v_pk_add_f32 v[126:127], v[126:127], v[142:143]
	v_pk_fma_f32 v[142:143], v[36:37], v[124:125], v[150:151] neg_lo:[0,0,1]
	v_pk_add_f32 v[124:125], v[128:129], v[144:145]
	v_pk_fma_f32 v[144:145], v[30:31], v[130:131], v[236:237] neg_lo:[0,0,1]
	v_pk_add_f32 v[128:129], v[146:147], v[120:121] neg_lo:[0,1] neg_hi:[0,1]
	v_pk_add_f32 v[130:131], v[114:115], v[122:123] neg_lo:[0,1] neg_hi:[0,1]
	v_pk_add_f32 v[150:151], v[116:117], v[126:127] neg_lo:[0,1] neg_hi:[0,1]
	v_pk_add_f32 v[236:237], v[118:119], v[124:125] neg_lo:[0,1] neg_hi:[0,1]
	v_pk_add_f32 v[238:239], v[148:149], v[138:139] neg_lo:[0,1] neg_hi:[0,1]
	v_pk_add_f32 v[240:241], v[132:133], v[140:141] neg_lo:[0,1] neg_hi:[0,1]
	v_pk_add_f32 v[242:243], v[134:135], v[142:143] neg_lo:[0,1] neg_hi:[0,1]
	v_pk_add_f32 v[244:245], v[136:137], v[144:145] neg_lo:[0,1] neg_hi:[0,1]
	v_pk_mul_f32 v[246:247], v[56:57], v[128:129]
	v_pk_add_f32 v[120:121], v[120:121], v[146:147]
	v_pk_mul_f32 v[146:147], v[66:67], v[130:131]
	v_pk_fma_f32 v[128:129], v[54:55], v[128:129], v[246:247] op_sel:[0,0,1] op_sel_hi:[1,1,0] neg_hi:[0,0,1]
	v_pk_mul_f32 v[246:247], v[70:71], v[150:151]
	v_pk_add_f32 v[114:115], v[114:115], v[122:123]
	v_pk_mul_f32 v[122:123], v[60:61], v[236:237]
	v_pk_fma_f32 v[130:131], v[64:65], v[130:131], v[146:147] op_sel:[0,0,1] op_sel_hi:[1,1,0] neg_lo:[0,0,1]
	v_pk_mul_f32 v[146:147], v[56:57], v[238:239]
	v_pk_add_f32 v[116:117], v[116:117], v[126:127]
	v_pk_mul_f32 v[126:127], v[66:67], v[240:241]
	v_pk_fma_f32 v[150:151], v[68:69], v[150:151], v[246:247] op_sel:[0,0,1] op_sel_hi:[1,1,0] neg_lo:[0,0,1]
	v_pk_mul_f32 v[246:247], v[70:71], v[242:243]
	v_pk_add_f32 v[118:119], v[118:119], v[124:125]
	v_pk_mul_f32 v[124:125], v[60:61], v[244:245]
	v_pk_fma_f32 v[122:123], v[62:63], v[236:237], v[122:123] op_sel:[0,0,1] op_sel_hi:[1,1,0] neg_lo:[0,0,1]
	v_pk_add_f32 v[138:139], v[138:139], v[148:149]
	v_pk_fma_f32 v[148:149], v[54:55], v[238:239], v[146:147] op_sel:[0,0,1] op_sel_hi:[1,1,0] neg_hi:[0,0,1]
	v_pk_add_f32 v[132:133], v[132:133], v[140:141]
	v_pk_fma_f32 v[140:141], v[64:65], v[240:241], v[126:127] op_sel:[0,0,1] op_sel_hi:[1,1,0] neg_lo:[0,0,1]
	v_pk_add_f32 v[126:127], v[134:135], v[142:143]
	v_pk_fma_f32 v[142:143], v[68:69], v[242:243], v[246:247] op_sel:[0,0,1] op_sel_hi:[1,1,0] neg_lo:[0,0,1]
	v_pk_add_f32 v[134:135], v[136:137], v[144:145]
	v_pk_fma_f32 v[144:145], v[62:63], v[244:245], v[124:125] op_sel:[0,0,1] op_sel_hi:[1,1,0] neg_lo:[0,0,1]
	v_pk_add_f32 v[124:125], v[120:121], v[116:117] neg_lo:[0,1] neg_hi:[0,1]
	v_pk_add_f32 v[136:137], v[114:115], v[118:119] neg_lo:[0,1] neg_hi:[0,1]
	v_pk_add_f32 v[146:147], v[128:129], v[150:151] neg_lo:[0,1] neg_hi:[0,1]
	v_pk_add_f32 v[236:237], v[130:131], v[122:123] neg_lo:[0,1] neg_hi:[0,1]
	v_pk_add_f32 v[238:239], v[138:139], v[126:127] neg_lo:[0,1] neg_hi:[0,1]
	v_pk_add_f32 v[240:241], v[132:133], v[134:135] neg_lo:[0,1] neg_hi:[0,1]
	v_pk_add_f32 v[242:243], v[148:149], v[142:143] neg_lo:[0,1] neg_hi:[0,1]
	v_pk_add_f32 v[244:245], v[140:141], v[144:145] neg_lo:[0,1] neg_hi:[0,1]
	v_pk_mul_f32 v[246:247], v[74:75], v[124:125]
	v_pk_add_f32 v[116:117], v[116:117], v[120:121]
	v_pk_mul_f32 v[120:121], v[78:79], v[136:137]
	v_pk_fma_f32 v[124:125], v[72:73], v[124:125], v[246:247] op_sel:[0,0,1] op_sel_hi:[1,1,0] neg_hi:[0,0,1]
	v_pk_mul_f32 v[246:247], v[74:75], v[146:147]
	v_pk_add_f32 v[114:115], v[114:115], v[118:119]
	v_pk_mul_f32 v[118:119], v[78:79], v[236:237]
	v_pk_fma_f32 v[120:121], v[76:77], v[136:137], v[120:121] op_sel:[0,0,1] op_sel_hi:[1,1,0] neg_lo:[0,0,1]
	v_pk_mul_f32 v[136:137], v[74:75], v[238:239]
	v_pk_add_f32 v[128:129], v[150:151], v[128:129]
	v_pk_mul_f32 v[150:151], v[78:79], v[240:241]
	v_pk_fma_f32 v[146:147], v[72:73], v[146:147], v[246:247] op_sel:[0,0,1] op_sel_hi:[1,1,0] neg_hi:[0,0,1]
	v_pk_mul_f32 v[246:247], v[74:75], v[242:243]
	v_pk_add_f32 v[122:123], v[130:131], v[122:123]
	v_pk_mul_f32 v[130:131], v[78:79], v[244:245]
	v_pk_fma_f32 v[118:119], v[76:77], v[236:237], v[118:119] op_sel:[0,0,1] op_sel_hi:[1,1,0] neg_lo:[0,0,1]
	v_pk_add_f32 v[126:127], v[126:127], v[138:139]
	v_pk_fma_f32 v[136:137], v[72:73], v[238:239], v[136:137] op_sel:[0,0,1] op_sel_hi:[1,1,0] neg_hi:[0,0,1]
	v_pk_add_f32 v[132:133], v[132:133], v[134:135]
	v_pk_fma_f32 v[134:135], v[76:77], v[240:241], v[150:151] op_sel:[0,0,1] op_sel_hi:[1,1,0] neg_lo:[0,0,1]
	v_pk_add_f32 v[138:139], v[142:143], v[148:149]
	v_pk_fma_f32 v[148:149], v[72:73], v[242:243], v[246:247] op_sel:[0,0,1] op_sel_hi:[1,1,0] neg_hi:[0,0,1]
	v_pk_add_f32 v[140:141], v[140:141], v[144:145]
	v_pk_fma_f32 v[144:145], v[76:77], v[244:245], v[130:131] op_sel:[0,0,1] op_sel_hi:[1,1,0] neg_lo:[0,0,1]
	v_pk_add_f32 v[130:131], v[116:117], v[114:115] neg_lo:[0,1] neg_hi:[0,1]
	v_pk_add_f32 v[142:143], v[124:125], v[120:121] neg_lo:[0,1] neg_hi:[0,1]
	v_pk_add_f32 v[150:151], v[128:129], v[122:123] neg_lo:[0,1] neg_hi:[0,1]
	v_pk_add_f32 v[236:237], v[146:147], v[118:119] neg_lo:[0,1] neg_hi:[0,1]
	v_pk_add_f32 v[238:239], v[126:127], v[132:133] neg_lo:[0,1] neg_hi:[0,1]
	v_pk_add_f32 v[240:241], v[136:137], v[134:135] neg_lo:[0,1] neg_hi:[0,1]
	v_pk_add_f32 v[242:243], v[138:139], v[140:141] neg_lo:[0,1] neg_hi:[0,1]
	v_pk_add_f32 v[244:245], v[148:149], v[144:145] neg_lo:[0,1] neg_hi:[0,1]
	v_pk_mul_f32 v[246:247], v[82:83], v[130:131]
	v_pk_add_f32 v[114:115], v[114:115], v[116:117]
	v_pk_mul_f32 v[116:117], v[82:83], v[142:143]
	v_pk_fma_f32 v[130:131], v[80:81], v[130:131], v[246:247] op_sel:[0,0,1] op_sel_hi:[1,1,0] neg_hi:[0,0,1]
	v_pk_mul_f32 v[246:247], v[82:83], v[150:151]
	v_pk_add_f32 v[120:121], v[120:121], v[124:125]
	v_pk_mul_f32 v[124:125], v[82:83], v[236:237]
	v_pk_fma_f32 v[116:117], v[80:81], v[142:143], v[116:117] op_sel:[0,0,1] op_sel_hi:[1,1,0] neg_hi:[0,0,1]
	v_pk_mul_f32 v[142:143], v[82:83], v[238:239]
	v_pk_add_f32 v[128:129], v[122:123], v[128:129]
	v_pk_mul_f32 v[122:123], v[82:83], v[240:241]
	v_pk_fma_f32 v[150:151], v[80:81], v[150:151], v[246:247] op_sel:[0,0,1] op_sel_hi:[1,1,0] neg_hi:[0,0,1]
	v_pk_mul_f32 v[246:247], v[82:83], v[242:243]
	v_pk_add_f32 v[118:119], v[118:119], v[146:147]
	v_pk_mul_f32 v[146:147], v[82:83], v[244:245]
	v_pk_fma_f32 v[124:125], v[80:81], v[236:237], v[124:125] op_sel:[0,0,1] op_sel_hi:[1,1,0] neg_hi:[0,0,1]
	v_pk_add_f32 v[126:127], v[132:133], v[126:127]
	v_pk_fma_f32 v[132:133], v[80:81], v[238:239], v[142:143] op_sel:[0,0,1] op_sel_hi:[1,1,0] neg_hi:[0,0,1]
	v_pk_add_f32 v[134:135], v[134:135], v[136:137]
	v_pk_fma_f32 v[122:123], v[80:81], v[240:241], v[122:123] op_sel:[0,0,1] op_sel_hi:[1,1,0] neg_hi:[0,0,1]
	v_pk_add_f32 v[136:137], v[140:141], v[138:139]
	v_pk_fma_f32 v[138:139], v[80:81], v[242:243], v[246:247] op_sel:[0,0,1] op_sel_hi:[1,1,0] neg_hi:[0,0,1]
	v_pk_add_f32 v[140:141], v[144:145], v[148:149]
	v_pk_fma_f32 v[144:145], v[80:81], v[244:245], v[146:147] op_sel:[0,0,1] op_sel_hi:[1,1,0] neg_hi:[0,0,1]
	ds_write2_b64 v152, v[114:115], v[130:131] offset1:4
	ds_write2_b64 v152, v[120:121], v[116:117] offset0:8 offset1:12
	ds_write2_b64 v152, v[128:129], v[150:151] offset0:16 offset1:20
	ds_write2_b64 v152, v[118:119], v[124:125] offset0:24 offset1:28
	ds_write2_b64 v153, v[126:127], v[132:133] offset0:32 offset1:36
	ds_write2_b64 v153, v[134:135], v[122:123] offset0:40 offset1:44
	ds_write2_b64 v153, v[136:137], v[138:139] offset0:48 offset1:52
	ds_write2_b64 v153, v[140:141], v[144:145] offset0:56 offset1:60
	s_andn2_b64 exec, exec, s[10:11]
	s_cbranch_execnz .LBB0_649

.LBB0_666:
	v_and_or_b32 v140, v111, s42, v0
	v_or_b32_e32 v128, 0x200, v140
	v_ashrrev_i32_e32 v114, 5, v140
	v_lshl_add_u32 v141, v140, 3, 0
	v_ashrrev_i32_e32 v128, 5, v128
	v_lshl_add_u32 v152, v114, 3, v141
	v_or_b32_e32 v114, 64, v140
	v_or_b32_e32 v116, 0x80, v140
	v_or_b32_e32 v118, 0xc0, v140
	v_or_b32_e32 v120, 0x100, v140
	v_or_b32_e32 v122, 0x140, v140
	v_or_b32_e32 v124, 0x180, v140
	v_or_b32_e32 v126, 0x1c0, v140
	v_lshl_add_u32 v160, v128, 3, v141
	v_or_b32_e32 v128, 0x240, v140
	v_or_b32_e32 v130, 0x280, v140
	v_or_b32_e32 v132, 0x2c0, v140
	v_or_b32_e32 v134, 0x300, v140
	v_or_b32_e32 v136, 0x340, v140
	v_or_b32_e32 v138, 0x380, v140
	v_or_b32_e32 v140, 0x3c0, v140
	v_ashrrev_i32_e32 v114, 5, v114
	v_ashrrev_i32_e32 v116, 5, v116
	v_ashrrev_i32_e32 v118, 5, v118
	v_ashrrev_i32_e32 v120, 5, v120
	v_ashrrev_i32_e32 v122, 5, v122
	v_ashrrev_i32_e32 v124, 5, v124
	v_ashrrev_i32_e32 v126, 5, v126
	v_ashrrev_i32_e32 v128, 5, v128
	v_ashrrev_i32_e32 v130, 5, v130
	v_ashrrev_i32_e32 v132, 5, v132
	v_ashrrev_i32_e32 v134, 5, v134
	v_ashrrev_i32_e32 v136, 5, v136
	v_ashrrev_i32_e32 v138, 5, v138
	v_ashrrev_i32_e32 v140, 5, v140
	v_lshl_add_u32 v153, v114, 3, v141
	v_lshl_add_u32 v154, v116, 3, v141
	v_lshl_add_u32 v155, v118, 3, v141
	v_lshl_add_u32 v156, v120, 3, v141
	v_lshl_add_u32 v157, v122, 3, v141
	v_lshl_add_u32 v158, v124, 3, v141
	v_lshl_add_u32 v159, v126, 3, v141
	v_lshl_add_u32 v161, v128, 3, v141
	v_lshl_add_u32 v162, v130, 3, v141
	v_lshl_add_u32 v163, v132, 3, v141
	v_lshl_add_u32 v164, v134, 3, v141
	v_lshl_add_u32 v165, v136, 3, v141
	v_lshl_add_u32 v166, v138, 3, v141
	v_lshl_add_u32 v167, v140, 3, v141
	ds_read_b64 v[114:115], v153 offset:512
	ds_read_b64 v[116:117], v154 offset:1024
	ds_read_b64 v[118:119], v155 offset:1536
	ds_read_b64 v[120:121], v156 offset:2048
	ds_read_b64 v[122:123], v157 offset:2560
	ds_read_b64 v[124:125], v158 offset:3072
	ds_read_b64 v[126:127], v159 offset:3584
	ds_read_b64 v[128:129], v161 offset:4608
	ds_read_b64 v[130:131], v162 offset:5120
	ds_read_b64 v[132:133], v163 offset:5632
	ds_read_b64 v[134:135], v164 offset:6144
	ds_read_b64 v[136:137], v165 offset:6656
	ds_read_b64 v[138:139], v166 offset:7168
	ds_read_b64 v[140:141], v167 offset:7680
	ds_read_b64 v[142:143], v160 offset:4096
	ds_read_b64 v[144:145], v152
	v_add_u32_e32 v25, 0x200, v25
	v_cmp_lt_i32_e32 vcc, s35, v25
	v_add_u32_e32 v111, 0x2000, v111
	s_or_b64 s[12:13], vcc, s[12:13]
	s_waitcnt lgkmcnt(0)
	v_pk_add_f32 v[146:147], v[144:145], v[142:143] neg_lo:[0,1] neg_hi:[0,1]
	v_pk_add_f32 v[148:149], v[114:115], v[128:129] neg_lo:[0,1] neg_hi:[0,1]
	v_pk_add_f32 v[150:151], v[116:117], v[130:131] neg_lo:[0,1] neg_hi:[0,1]
	v_pk_add_f32 v[236:237], v[118:119], v[132:133] neg_lo:[0,1] neg_hi:[0,1]
	v_pk_add_f32 v[238:239], v[120:121], v[134:135] neg_lo:[0,1] neg_hi:[0,1]
	v_pk_add_f32 v[240:241], v[122:123], v[136:137] neg_lo:[0,1] neg_hi:[0,1]
	v_pk_add_f32 v[242:243], v[124:125], v[138:139] neg_lo:[0,1] neg_hi:[0,1]
	v_pk_add_f32 v[244:245], v[126:127], v[140:141] neg_lo:[0,1] neg_hi:[0,1]
	v_pk_mul_f32 v[246:247], v[20:21], v[146:147] op_sel:[0,1] op_sel_hi:[1,0]
	v_pk_add_f32 v[142:143], v[142:143], v[144:145]
	v_pk_mul_f32 v[144:145], v[40:41], v[148:149] op_sel:[0,1] op_sel_hi:[1,0]
	v_pk_fma_f32 v[146:147], v[2:3], v[146:147], v[246:247] neg_hi:[0,0,1]
	v_pk_mul_f32 v[246:247], v[44:45], v[150:151] op_sel:[0,1] op_sel_hi:[1,0]
	v_pk_add_f32 v[114:115], v[114:115], v[128:129]
	v_pk_mul_f32 v[128:129], v[48:49], v[236:237] op_sel:[0,1] op_sel_hi:[1,0]
	v_pk_fma_f32 v[144:145], v[38:39], v[148:149], v[144:145] neg_lo:[0,0,1]
	v_pk_mul_f32 v[148:149], v[52:53], v[238:239] op_sel:[0,1] op_sel_hi:[1,0]
	v_pk_add_f32 v[116:117], v[116:117], v[130:131]
	v_pk_mul_f32 v[130:131], v[22:23], v[240:241] op_sel:[0,1] op_sel_hi:[1,0]
	v_pk_fma_f32 v[150:151], v[42:43], v[150:151], v[246:247] neg_lo:[0,0,1]
	v_pk_mul_f32 v[246:247], v[34:35], v[242:243] op_sel:[0,1] op_sel_hi:[1,0]
	v_pk_add_f32 v[118:119], v[118:119], v[132:133]
	v_pk_mul_f32 v[132:133], v[58:59], v[244:245] op_sel:[0,1] op_sel_hi:[1,0]
	v_pk_fma_f32 v[128:129], v[32:33], v[236:237], v[128:129] neg_lo:[0,0,1]
	v_pk_add_f32 v[120:121], v[120:121], v[134:135]
	v_pk_fma_f32 v[134:135], v[50:51], v[238:239], v[148:149] neg_lo:[0,0,1]
	v_pk_add_f32 v[122:123], v[122:123], v[136:137]
	v_pk_fma_f32 v[136:137], v[46:47], v[240:241], v[130:131] neg_lo:[0,0,1]
	v_pk_add_f32 v[124:125], v[124:125], v[138:139]
	v_pk_fma_f32 v[138:139], v[36:37], v[242:243], v[246:247] neg_lo:[0,0,1]
	v_pk_add_f32 v[126:127], v[126:127], v[140:141]
	v_pk_fma_f32 v[140:141], v[30:31], v[244:245], v[132:133] neg_lo:[0,0,1]
	v_pk_add_f32 v[130:131], v[142:143], v[120:121] neg_lo:[0,1] neg_hi:[0,1]
	v_pk_add_f32 v[132:133], v[114:115], v[122:123] neg_lo:[0,1] neg_hi:[0,1]
	v_pk_add_f32 v[148:149], v[116:117], v[124:125] neg_lo:[0,1] neg_hi:[0,1]
	v_pk_add_f32 v[236:237], v[118:119], v[126:127] neg_lo:[0,1] neg_hi:[0,1]
	v_pk_add_f32 v[238:239], v[146:147], v[134:135] neg_lo:[0,1] neg_hi:[0,1]
	v_pk_add_f32 v[240:241], v[144:145], v[136:137] neg_lo:[0,1] neg_hi:[0,1]
	v_pk_add_f32 v[242:243], v[150:151], v[138:139] neg_lo:[0,1] neg_hi:[0,1]
	v_pk_add_f32 v[244:245], v[128:129], v[140:141] neg_lo:[0,1] neg_hi:[0,1]
	v_pk_mul_f32 v[246:247], v[56:57], v[130:131]
	v_pk_add_f32 v[120:121], v[120:121], v[142:143]
	v_pk_mul_f32 v[142:143], v[66:67], v[132:133]
	v_pk_fma_f32 v[130:131], v[54:55], v[130:131], v[246:247] op_sel:[0,0,1] op_sel_hi:[1,1,0] neg_hi:[0,0,1]
	v_pk_mul_f32 v[246:247], v[70:71], v[148:149]
	v_pk_add_f32 v[114:115], v[114:115], v[122:123]
	v_pk_mul_f32 v[122:123], v[60:61], v[236:237]
	v_pk_fma_f32 v[142:143], v[64:65], v[132:133], v[142:143] op_sel:[0,0,1] op_sel_hi:[1,1,0] neg_lo:[0,0,1]
	v_pk_mul_f32 v[132:133], v[56:57], v[238:239]
	v_pk_add_f32 v[116:117], v[116:117], v[124:125]
	v_pk_mul_f32 v[124:125], v[66:67], v[240:241]
	v_pk_fma_f32 v[148:149], v[68:69], v[148:149], v[246:247] op_sel:[0,0,1] op_sel_hi:[1,1,0] neg_lo:[0,0,1]
	v_pk_mul_f32 v[246:247], v[70:71], v[242:243]
	v_pk_add_f32 v[118:119], v[118:119], v[126:127]
	v_pk_mul_f32 v[126:127], v[60:61], v[244:245]
	v_pk_fma_f32 v[122:123], v[62:63], v[236:237], v[122:123] op_sel:[0,0,1] op_sel_hi:[1,1,0] neg_lo:[0,0,1]
	v_pk_add_f32 v[134:135], v[134:135], v[146:147]
	v_pk_fma_f32 v[132:133], v[54:55], v[238:239], v[132:133] op_sel:[0,0,1] op_sel_hi:[1,1,0] neg_hi:[0,0,1]
	v_pk_add_f32 v[136:137], v[144:145], v[136:137]
	v_pk_fma_f32 v[144:145], v[64:65], v[240:241], v[124:125] op_sel:[0,0,1] op_sel_hi:[1,1,0] neg_lo:[0,0,1]
	v_pk_add_f32 v[124:125], v[150:151], v[138:139]
	v_pk_fma_f32 v[138:139], v[68:69], v[242:243], v[246:247] op_sel:[0,0,1] op_sel_hi:[1,1,0] neg_lo:[0,0,1]
	v_pk_add_f32 v[128:129], v[128:129], v[140:141]
	v_pk_fma_f32 v[140:141], v[62:63], v[244:245], v[126:127] op_sel:[0,0,1] op_sel_hi:[1,1,0] neg_lo:[0,0,1]
	v_pk_add_f32 v[126:127], v[120:121], v[116:117] neg_lo:[0,1] neg_hi:[0,1]
	v_pk_add_f32 v[146:147], v[114:115], v[118:119] neg_lo:[0,1] neg_hi:[0,1]
	v_pk_add_f32 v[150:151], v[130:131], v[148:149] neg_lo:[0,1] neg_hi:[0,1]
	v_pk_add_f32 v[236:237], v[142:143], v[122:123] neg_lo:[0,1] neg_hi:[0,1]
	v_pk_add_f32 v[238:239], v[134:135], v[124:125] neg_lo:[0,1] neg_hi:[0,1]
	v_pk_add_f32 v[240:241], v[136:137], v[128:129] neg_lo:[0,1] neg_hi:[0,1]
	v_pk_add_f32 v[242:243], v[132:133], v[138:139] neg_lo:[0,1] neg_hi:[0,1]
	v_pk_add_f32 v[244:245], v[144:145], v[140:141] neg_lo:[0,1] neg_hi:[0,1]
	v_pk_mul_f32 v[246:247], v[74:75], v[126:127]
	v_pk_add_f32 v[116:117], v[116:117], v[120:121]
	v_pk_mul_f32 v[120:121], v[78:79], v[146:147]
	v_pk_fma_f32 v[126:127], v[72:73], v[126:127], v[246:247] op_sel:[0,0,1] op_sel_hi:[1,1,0] neg_hi:[0,0,1]
	v_pk_mul_f32 v[246:247], v[74:75], v[150:151]
	v_pk_add_f32 v[114:115], v[114:115], v[118:119]
	v_pk_mul_f32 v[118:119], v[78:79], v[236:237]
	v_pk_fma_f32 v[120:121], v[76:77], v[146:147], v[120:121] op_sel:[0,0,1] op_sel_hi:[1,1,0] neg_lo:[0,0,1]
	v_pk_mul_f32 v[146:147], v[74:75], v[238:239]
	v_pk_add_f32 v[130:131], v[148:149], v[130:131]
	v_pk_mul_f32 v[148:149], v[78:79], v[240:241]
	v_pk_fma_f32 v[150:151], v[72:73], v[150:151], v[246:247] op_sel:[0,0,1] op_sel_hi:[1,1,0] neg_hi:[0,0,1]
	v_pk_mul_f32 v[246:247], v[74:75], v[242:243]
	v_pk_add_f32 v[122:123], v[142:143], v[122:123]
	v_pk_mul_f32 v[142:143], v[78:79], v[244:245]
	v_pk_fma_f32 v[118:119], v[76:77], v[236:237], v[118:119] op_sel:[0,0,1] op_sel_hi:[1,1,0] neg_lo:[0,0,1]
	v_pk_add_f32 v[124:125], v[124:125], v[134:135]
	v_pk_fma_f32 v[134:135], v[72:73], v[238:239], v[146:147] op_sel:[0,0,1] op_sel_hi:[1,1,0] neg_hi:[0,0,1]
	v_pk_add_f32 v[128:129], v[136:137], v[128:129]
	v_pk_fma_f32 v[136:137], v[76:77], v[240:241], v[148:149] op_sel:[0,0,1] op_sel_hi:[1,1,0] neg_lo:[0,0,1]
	v_pk_add_f32 v[132:133], v[138:139], v[132:133]
	v_pk_fma_f32 v[148:149], v[72:73], v[242:243], v[246:247] op_sel:[0,0,1] op_sel_hi:[1,1,0] neg_hi:[0,0,1]
	v_pk_add_f32 v[138:139], v[144:145], v[140:141]
	v_pk_fma_f32 v[144:145], v[76:77], v[244:245], v[142:143] op_sel:[0,0,1] op_sel_hi:[1,1,0] neg_lo:[0,0,1]
	v_pk_add_f32 v[140:141], v[116:117], v[114:115] neg_lo:[0,1] neg_hi:[0,1]
	v_pk_add_f32 v[142:143], v[126:127], v[120:121] neg_lo:[0,1] neg_hi:[0,1]
	v_pk_add_f32 v[146:147], v[130:131], v[122:123] neg_lo:[0,1] neg_hi:[0,1]
	v_pk_add_f32 v[236:237], v[150:151], v[118:119] neg_lo:[0,1] neg_hi:[0,1]
	v_pk_add_f32 v[238:239], v[124:125], v[128:129] neg_lo:[0,1] neg_hi:[0,1]
	v_pk_add_f32 v[240:241], v[134:135], v[136:137] neg_lo:[0,1] neg_hi:[0,1]
	v_pk_add_f32 v[242:243], v[132:133], v[138:139] neg_lo:[0,1] neg_hi:[0,1]
	v_pk_add_f32 v[244:245], v[148:149], v[144:145] neg_lo:[0,1] neg_hi:[0,1]
	v_pk_mul_f32 v[246:247], v[82:83], v[140:141]
	v_pk_add_f32 v[114:115], v[114:115], v[116:117]
	v_pk_mul_f32 v[116:117], v[82:83], v[142:143]
	v_pk_fma_f32 v[140:141], v[80:81], v[140:141], v[246:247] op_sel:[0,0,1] op_sel_hi:[1,1,0] neg_hi:[0,0,1]
	v_pk_mul_f32 v[246:247], v[82:83], v[146:147]
	v_pk_add_f32 v[120:121], v[120:121], v[126:127]
	v_pk_mul_f32 v[126:127], v[82:83], v[236:237]
	v_pk_fma_f32 v[116:117], v[80:81], v[142:143], v[116:117] op_sel:[0,0,1] op_sel_hi:[1,1,0] neg_hi:[0,0,1]
	v_pk_mul_f32 v[142:143], v[82:83], v[238:239]
	v_pk_add_f32 v[122:123], v[122:123], v[130:131]
	v_pk_mul_f32 v[130:131], v[82:83], v[240:241]
	v_pk_fma_f32 v[146:147], v[80:81], v[146:147], v[246:247] op_sel:[0,0,1] op_sel_hi:[1,1,0] neg_hi:[0,0,1]
	v_pk_mul_f32 v[246:247], v[82:83], v[242:243]
	v_pk_add_f32 v[118:119], v[118:119], v[150:151]
	v_pk_mul_f32 v[150:151], v[82:83], v[244:245]
	v_pk_fma_f32 v[126:127], v[80:81], v[236:237], v[126:127] op_sel:[0,0,1] op_sel_hi:[1,1,0] neg_hi:[0,0,1]
	v_pk_add_f32 v[124:125], v[128:129], v[124:125]
	v_pk_fma_f32 v[142:143], v[80:81], v[238:239], v[142:143] op_sel:[0,0,1] op_sel_hi:[1,1,0] neg_hi:[0,0,1]
	v_pk_add_f32 v[128:129], v[136:137], v[134:135]
	v_pk_fma_f32 v[134:135], v[80:81], v[240:241], v[130:131] op_sel:[0,0,1] op_sel_hi:[1,1,0] neg_hi:[0,0,1]
	v_pk_add_f32 v[130:131], v[138:139], v[132:133]
	v_pk_fma_f32 v[132:133], v[80:81], v[242:243], v[246:247] op_sel:[0,0,1] op_sel_hi:[1,1,0] neg_hi:[0,0,1]
	v_pk_add_f32 v[136:137], v[144:145], v[148:149]
	v_pk_fma_f32 v[144:145], v[80:81], v[244:245], v[150:151] op_sel:[0,0,1] op_sel_hi:[1,1,0] neg_hi:[0,0,1]
	ds_write_b64 v152, v[114:115]
	ds_write_b64 v153, v[140:141] offset:512
	ds_write_b64 v154, v[120:121] offset:1024
	ds_write_b64 v155, v[116:117] offset:1536
	ds_write_b64 v156, v[122:123] offset:2048
	ds_write_b64 v157, v[146:147] offset:2560
	ds_write_b64 v158, v[118:119] offset:3072
	ds_write_b64 v159, v[126:127] offset:3584
	ds_write_b64 v160, v[124:125] offset:4096
	ds_write_b64 v161, v[142:143] offset:4608
	ds_write_b64 v162, v[128:129] offset:5120
	ds_write_b64 v163, v[134:135] offset:5632
	ds_write_b64 v164, v[130:131] offset:6144
	ds_write_b64 v165, v[132:133] offset:6656
	ds_write_b64 v166, v[136:137] offset:7168
	ds_write_b64 v167, v[144:145] offset:7680
	s_andn2_b64 exec, exec, s[12:13]
	s_cbranch_execnz .LBB0_666

.LBB0_669:
	v_and_b32_e32 v130, 0xffffffc0, v111
	v_or_b32_e32 v114, v130, v0
	v_lshl_add_u32 v131, v114, 3, 0
	v_ashrrev_i32_e32 v114, 2, v130
	v_or_b32_e32 v130, 32, v130
	v_ashrrev_i32_e32 v130, 5, v130
	v_add_u32_e32 v152, v131, v114
	v_lshl_add_u32 v153, v130, 3, v131
	ds_read2_b64 v[114:117], v152 offset1:4
	ds_read2_b64 v[118:121], v152 offset0:8 offset1:12
	ds_read2_b64 v[122:125], v152 offset0:16 offset1:20
	ds_read2_b64 v[126:129], v152 offset0:24 offset1:28
	ds_read2_b64 v[130:133], v153 offset0:32 offset1:36
	ds_read2_b64 v[134:137], v153 offset0:40 offset1:44
	ds_read2_b64 v[138:141], v153 offset0:48 offset1:52
	ds_read2_b64 v[142:145], v153 offset0:56 offset1:60
	v_add_u32_e32 v25, 0x200, v25
	s_waitcnt lgkmcnt(3)
	v_pk_add_f32 v[146:147], v[130:131], v[114:115]
	v_pk_add_f32 v[114:115], v[114:115], v[130:131] neg_lo:[0,1] neg_hi:[0,1]
	v_cmp_lt_i32_e32 vcc, s35, v25
	v_pk_mul_f32 v[130:131], v[20:21], v[114:115] op_sel:[0,1] op_sel_hi:[1,0]
	v_add_u32_e32 v111, 0x2000, v111
	v_pk_fma_f32 v[148:149], v[2:3], v[114:115], v[130:131] neg_hi:[0,0,1]
	s_or_b64 s[12:13], vcc, s[12:13]
	v_pk_add_f32 v[114:115], v[116:117], v[132:133]
	v_pk_add_f32 v[116:117], v[116:117], v[132:133] neg_lo:[0,1] neg_hi:[0,1]
	s_nop 0
	v_pk_mul_f32 v[130:131], v[40:41], v[116:117] op_sel:[0,1] op_sel_hi:[1,0]
	s_nop 0
	v_pk_fma_f32 v[132:133], v[38:39], v[116:117], v[130:131] neg_lo:[0,0,1]
	s_waitcnt lgkmcnt(2)
	v_pk_add_f32 v[116:117], v[118:119], v[134:135]
	v_pk_add_f32 v[118:119], v[118:119], v[134:135] neg_lo:[0,1] neg_hi:[0,1]
	s_nop 0
	v_pk_mul_f32 v[130:131], v[44:45], v[118:119] op_sel:[0,1] op_sel_hi:[1,0]
	s_nop 0
	v_pk_fma_f32 v[134:135], v[42:43], v[118:119], v[130:131] neg_lo:[0,0,1]
	v_pk_add_f32 v[118:119], v[120:121], v[136:137]
	v_pk_add_f32 v[120:121], v[120:121], v[136:137] neg_lo:[0,1] neg_hi:[0,1]
	s_nop 0
	v_pk_mul_f32 v[130:131], v[48:49], v[120:121] op_sel:[0,1] op_sel_hi:[1,0]
	s_nop 0
	v_pk_fma_f32 v[136:137], v[32:33], v[120:121], v[130:131] neg_lo:[0,0,1]
	s_waitcnt lgkmcnt(1)
	v_pk_add_f32 v[120:121], v[122:123], v[138:139]
	v_pk_add_f32 v[122:123], v[122:123], v[138:139] neg_lo:[0,1] neg_hi:[0,1]
	s_nop 0
	v_pk_mul_f32 v[130:131], v[52:53], v[122:123] op_sel:[0,1] op_sel_hi:[1,0]
	s_nop 0
	v_pk_fma_f32 v[138:139], v[50:51], v[122:123], v[130:131] neg_lo:[0,0,1]
	v_pk_add_f32 v[122:123], v[124:125], v[140:141]
	v_pk_add_f32 v[124:125], v[124:125], v[140:141] neg_lo:[0,1] neg_hi:[0,1]
	s_nop 0
	v_pk_mul_f32 v[130:131], v[22:23], v[124:125] op_sel:[0,1] op_sel_hi:[1,0]
	s_nop 0
	v_pk_fma_f32 v[140:141], v[46:47], v[124:125], v[130:131] neg_lo:[0,0,1]
	s_waitcnt lgkmcnt(0)
	v_pk_add_f32 v[124:125], v[126:127], v[142:143] neg_lo:[0,1] neg_hi:[0,1]
	v_pk_add_f32 v[130:131], v[128:129], v[144:145] neg_lo:[0,1] neg_hi:[0,1]
	v_pk_mul_f32 v[150:151], v[34:35], v[124:125] op_sel:[0,1] op_sel_hi:[1,0]
	v_pk_mul_f32 v[236:237], v[58:59], v[130:131] op_sel:[0,1] op_sel_hi:[1,0]
	v_pk_add_f32 v[126:127], v[126:127], v[142:143]
	v_pk_fma_f32 v[142:143], v[36:37], v[124:125], v[150:151] neg_lo:[0,0,1]
	v_pk_add_f32 v[124:125], v[128:129], v[144:145]
	v_pk_fma_f32 v[144:145], v[30:31], v[130:131], v[236:237] neg_lo:[0,0,1]
	v_pk_add_f32 v[128:129], v[146:147], v[120:121] neg_lo:[0,1] neg_hi:[0,1]
	v_pk_add_f32 v[130:131], v[114:115], v[122:123] neg_lo:[0,1] neg_hi:[0,1]
	v_pk_add_f32 v[150:151], v[116:117], v[126:127] neg_lo:[0,1] neg_hi:[0,1]
	v_pk_add_f32 v[236:237], v[118:119], v[124:125] neg_lo:[0,1] neg_hi:[0,1]
	v_pk_add_f32 v[238:239], v[148:149], v[138:139] neg_lo:[0,1] neg_hi:[0,1]
	v_pk_add_f32 v[240:241], v[132:133], v[140:141] neg_lo:[0,1] neg_hi:[0,1]
	v_pk_add_f32 v[242:243], v[134:135], v[142:143] neg_lo:[0,1] neg_hi:[0,1]
	v_pk_add_f32 v[244:245], v[136:137], v[144:145] neg_lo:[0,1] neg_hi:[0,1]
	v_pk_mul_f32 v[246:247], v[56:57], v[128:129]
	v_pk_add_f32 v[120:121], v[120:121], v[146:147]
	v_pk_mul_f32 v[146:147], v[66:67], v[130:131]
	v_pk_fma_f32 v[128:129], v[54:55], v[128:129], v[246:247] op_sel:[0,0,1] op_sel_hi:[1,1,0] neg_hi:[0,0,1]
	v_pk_mul_f32 v[246:247], v[70:71], v[150:151]
	v_pk_add_f32 v[114:115], v[114:115], v[122:123]
	v_pk_mul_f32 v[122:123], v[60:61], v[236:237]
	v_pk_fma_f32 v[130:131], v[64:65], v[130:131], v[146:147] op_sel:[0,0,1] op_sel_hi:[1,1,0] neg_lo:[0,0,1]
	v_pk_mul_f32 v[146:147], v[56:57], v[238:239]
	v_pk_add_f32 v[116:117], v[116:117], v[126:127]
	v_pk_mul_f32 v[126:127], v[66:67], v[240:241]
	v_pk_fma_f32 v[150:151], v[68:69], v[150:151], v[246:247] op_sel:[0,0,1] op_sel_hi:[1,1,0] neg_lo:[0,0,1]
	v_pk_mul_f32 v[246:247], v[70:71], v[242:243]
	v_pk_add_f32 v[118:119], v[118:119], v[124:125]
	v_pk_mul_f32 v[124:125], v[60:61], v[244:245]
	v_pk_fma_f32 v[122:123], v[62:63], v[236:237], v[122:123] op_sel:[0,0,1] op_sel_hi:[1,1,0] neg_lo:[0,0,1]
	v_pk_add_f32 v[138:139], v[138:139], v[148:149]
	v_pk_fma_f32 v[148:149], v[54:55], v[238:239], v[146:147] op_sel:[0,0,1] op_sel_hi:[1,1,0] neg_hi:[0,0,1]
	v_pk_add_f32 v[132:133], v[132:133], v[140:141]
	v_pk_fma_f32 v[140:141], v[64:65], v[240:241], v[126:127] op_sel:[0,0,1] op_sel_hi:[1,1,0] neg_lo:[0,0,1]
	v_pk_add_f32 v[126:127], v[134:135], v[142:143]
	v_pk_fma_f32 v[142:143], v[68:69], v[242:243], v[246:247] op_sel:[0,0,1] op_sel_hi:[1,1,0] neg_lo:[0,0,1]
	v_pk_add_f32 v[134:135], v[136:137], v[144:145]
	v_pk_fma_f32 v[144:145], v[62:63], v[244:245], v[124:125] op_sel:[0,0,1] op_sel_hi:[1,1,0] neg_lo:[0,0,1]
	v_pk_add_f32 v[124:125], v[120:121], v[116:117] neg_lo:[0,1] neg_hi:[0,1]
	v_pk_add_f32 v[136:137], v[114:115], v[118:119] neg_lo:[0,1] neg_hi:[0,1]
	v_pk_add_f32 v[146:147], v[128:129], v[150:151] neg_lo:[0,1] neg_hi:[0,1]
	v_pk_add_f32 v[236:237], v[130:131], v[122:123] neg_lo:[0,1] neg_hi:[0,1]
	v_pk_add_f32 v[238:239], v[138:139], v[126:127] neg_lo:[0,1] neg_hi:[0,1]
	v_pk_add_f32 v[240:241], v[132:133], v[134:135] neg_lo:[0,1] neg_hi:[0,1]
	v_pk_add_f32 v[242:243], v[148:149], v[142:143] neg_lo:[0,1] neg_hi:[0,1]
	v_pk_add_f32 v[244:245], v[140:141], v[144:145] neg_lo:[0,1] neg_hi:[0,1]
	v_pk_mul_f32 v[246:247], v[74:75], v[124:125]
	v_pk_add_f32 v[116:117], v[116:117], v[120:121]
	v_pk_mul_f32 v[120:121], v[78:79], v[136:137]
	v_pk_fma_f32 v[124:125], v[72:73], v[124:125], v[246:247] op_sel:[0,0,1] op_sel_hi:[1,1,0] neg_hi:[0,0,1]
	v_pk_mul_f32 v[246:247], v[74:75], v[146:147]
	v_pk_add_f32 v[114:115], v[114:115], v[118:119]
	v_pk_mul_f32 v[118:119], v[78:79], v[236:237]
	v_pk_fma_f32 v[120:121], v[76:77], v[136:137], v[120:121] op_sel:[0,0,1] op_sel_hi:[1,1,0] neg_lo:[0,0,1]
	v_pk_mul_f32 v[136:137], v[74:75], v[238:239]
	v_pk_add_f32 v[128:129], v[150:151], v[128:129]
	v_pk_mul_f32 v[150:151], v[78:79], v[240:241]
	v_pk_fma_f32 v[146:147], v[72:73], v[146:147], v[246:247] op_sel:[0,0,1] op_sel_hi:[1,1,0] neg_hi:[0,0,1]
	v_pk_mul_f32 v[246:247], v[74:75], v[242:243]
	v_pk_add_f32 v[122:123], v[130:131], v[122:123]
	v_pk_mul_f32 v[130:131], v[78:79], v[244:245]
	v_pk_fma_f32 v[118:119], v[76:77], v[236:237], v[118:119] op_sel:[0,0,1] op_sel_hi:[1,1,0] neg_lo:[0,0,1]
	v_pk_add_f32 v[126:127], v[126:127], v[138:139]
	v_pk_fma_f32 v[136:137], v[72:73], v[238:239], v[136:137] op_sel:[0,0,1] op_sel_hi:[1,1,0] neg_hi:[0,0,1]
	v_pk_add_f32 v[132:133], v[132:133], v[134:135]
	v_pk_fma_f32 v[134:135], v[76:77], v[240:241], v[150:151] op_sel:[0,0,1] op_sel_hi:[1,1,0] neg_lo:[0,0,1]
	v_pk_add_f32 v[138:139], v[142:143], v[148:149]
	v_pk_fma_f32 v[148:149], v[72:73], v[242:243], v[246:247] op_sel:[0,0,1] op_sel_hi:[1,1,0] neg_hi:[0,0,1]
	v_pk_add_f32 v[140:141], v[140:141], v[144:145]
	v_pk_fma_f32 v[144:145], v[76:77], v[244:245], v[130:131] op_sel:[0,0,1] op_sel_hi:[1,1,0] neg_lo:[0,0,1]
	v_pk_add_f32 v[130:131], v[116:117], v[114:115] neg_lo:[0,1] neg_hi:[0,1]
	v_pk_add_f32 v[142:143], v[124:125], v[120:121] neg_lo:[0,1] neg_hi:[0,1]
	v_pk_add_f32 v[150:151], v[128:129], v[122:123] neg_lo:[0,1] neg_hi:[0,1]
	v_pk_add_f32 v[236:237], v[146:147], v[118:119] neg_lo:[0,1] neg_hi:[0,1]
	v_pk_add_f32 v[238:239], v[126:127], v[132:133] neg_lo:[0,1] neg_hi:[0,1]
	v_pk_add_f32 v[240:241], v[136:137], v[134:135] neg_lo:[0,1] neg_hi:[0,1]
	v_pk_add_f32 v[242:243], v[138:139], v[140:141] neg_lo:[0,1] neg_hi:[0,1]
	v_pk_add_f32 v[244:245], v[148:149], v[144:145] neg_lo:[0,1] neg_hi:[0,1]
	v_pk_mul_f32 v[246:247], v[82:83], v[130:131]
	v_pk_add_f32 v[114:115], v[114:115], v[116:117]
	v_pk_mul_f32 v[116:117], v[82:83], v[142:143]
	v_pk_fma_f32 v[130:131], v[80:81], v[130:131], v[246:247] op_sel:[0,0,1] op_sel_hi:[1,1,0] neg_hi:[0,0,1]
	v_pk_mul_f32 v[246:247], v[82:83], v[150:151]
	v_pk_add_f32 v[120:121], v[120:121], v[124:125]
	v_pk_mul_f32 v[124:125], v[82:83], v[236:237]
	v_pk_fma_f32 v[116:117], v[80:81], v[142:143], v[116:117] op_sel:[0,0,1] op_sel_hi:[1,1,0] neg_hi:[0,0,1]
	v_pk_mul_f32 v[142:143], v[82:83], v[238:239]
	v_pk_add_f32 v[128:129], v[122:123], v[128:129]
	v_pk_mul_f32 v[122:123], v[82:83], v[240:241]
	v_pk_fma_f32 v[150:151], v[80:81], v[150:151], v[246:247] op_sel:[0,0,1] op_sel_hi:[1,1,0] neg_hi:[0,0,1]
	v_pk_mul_f32 v[246:247], v[82:83], v[242:243]
	v_pk_add_f32 v[118:119], v[118:119], v[146:147]
	v_pk_mul_f32 v[146:147], v[82:83], v[244:245]
	v_pk_fma_f32 v[124:125], v[80:81], v[236:237], v[124:125] op_sel:[0,0,1] op_sel_hi:[1,1,0] neg_hi:[0,0,1]
	v_pk_add_f32 v[126:127], v[132:133], v[126:127]
	v_pk_fma_f32 v[132:133], v[80:81], v[238:239], v[142:143] op_sel:[0,0,1] op_sel_hi:[1,1,0] neg_hi:[0,0,1]
	v_pk_add_f32 v[134:135], v[134:135], v[136:137]
	v_pk_fma_f32 v[122:123], v[80:81], v[240:241], v[122:123] op_sel:[0,0,1] op_sel_hi:[1,1,0] neg_hi:[0,0,1]
	v_pk_add_f32 v[136:137], v[140:141], v[138:139]
	v_pk_fma_f32 v[138:139], v[80:81], v[242:243], v[246:247] op_sel:[0,0,1] op_sel_hi:[1,1,0] neg_hi:[0,0,1]
	v_pk_add_f32 v[140:141], v[144:145], v[148:149]
	v_pk_fma_f32 v[144:145], v[80:81], v[244:245], v[146:147] op_sel:[0,0,1] op_sel_hi:[1,1,0] neg_hi:[0,0,1]
	ds_write2_b64 v152, v[114:115], v[130:131] offset1:4
	ds_write2_b64 v152, v[120:121], v[116:117] offset0:8 offset1:12
	ds_write2_b64 v152, v[128:129], v[150:151] offset0:16 offset1:20
	ds_write2_b64 v152, v[118:119], v[124:125] offset0:24 offset1:28
	ds_write2_b64 v153, v[126:127], v[132:133] offset0:32 offset1:36
	ds_write2_b64 v153, v[134:135], v[122:123] offset0:40 offset1:44
	ds_write2_b64 v153, v[136:137], v[138:139] offset0:48 offset1:52
	ds_write2_b64 v153, v[140:141], v[144:145] offset0:56 offset1:60
	s_andn2_b64 exec, exec, s[12:13]
	s_cbranch_execnz .LBB0_669
